# same as previous, guard padded to 256 B so later hot loops keep their placement
# speedup vs baseline: 1.0066x; 1.0066x over previous
; __global__ void __launch_bounds__(256, 2) mega(Params p) {
;     ...
;     for (int rep = 0; rep < REP_2B; ++rep) {
;       bool first = true;
;       for (;;) {
;         int it;
;         if (first) { it = (int)blockIdx.x; first = false; }
;         else it = next_item(ctr + layer * 2 + 1 + 8 * rep, &slot) + (int)gridDim.x;
;         if (rep > 0) { it += PROBE_2B_LO; if (it >= PROBE_2B_HI) break; }
;         if (it >= 288 + 192 + 24 + 256 + 1536) break;
;         it = (it < 192) ? (it + 384) : ((it < 480) ? (it - 192) : ((it < 504) ? (it + 608) : ((it < 760) ? (it + 328) : (it + 352))));
.LBB0_354:
	s_or_b64 exec, exec, s[0:1]
	s_mul_i32 s0, s69, 12
	v_writelane_b32 v255, s0, 51
	v_readlane_b32 s2, v252, 0
	s_waitcnt lgkmcnt(0)
	s_barrier
	s_nop 0
	s_nop 0
	s_nop 0
	s_nop 0
	s_nop 0
	s_nop 0
	s_nop 0
	s_nop 0
	s_nop 0
	s_nop 0
	s_nop 0
	s_nop 0
	s_nop 0
	s_nop 0
	s_nop 0
	s_nop 0
	s_nop 0
	s_nop 0
	s_nop 0
	s_nop 0
	s_nop 0
	s_nop 0
	s_nop 0
	s_nop 0
	s_nop 0
	s_nop 0
	s_nop 0
	s_nop 0
	s_nop 0
	s_nop 0
	s_nop 0
	s_nop 0
	s_nop 0
	s_nop 0
	s_nop 0
	s_nop 0
	s_nop 0
	s_nop 0
	s_nop 0
	s_nop 0
	s_nop 0
	s_nop 0
	s_nop 0
	s_nop 0
	s_nop 0
	s_nop 0
	s_nop 0
	s_nop 0
	s_nop 0
	s_nop 0
	s_nop 0
	s_nop 0
	s_nop 0
	s_nop 0
	s_nop 0
	s_nop 0
	s_nop 0
	s_nop 0
	s_nop 0
	v_readlane_b32 s98, v255, 38
	s_cmp_eq_u32 s98, 0x200
	s_cbranch_scc0 .Lmap2b_done
	s_cmp_lt_u32 s2, 192
	s_cbranch_scc1 .Lmap2b_done
	s_cmp_lt_u32 s2, 224
	s_cbranch_scc0 .Lmap2b_a
	s_add_i32 s2, s2, 128
	s_branch .Lmap2b_done
